# S5 sample-item loop: next item's state and u loads prefetched while the current item is processed; counted vmcnt at the loop top
# speedup vs baseline: 1.0132x; 1.0025x over previous
.LBB0_1018:
	s_or_b64 exec, exec, s[6:7]
	s_and_saveexec_b64 s[10:11], s[4:5]
	s_cbranch_execz .LBB0_1031
	v_lshl_or_b32 v51, v149, 2, 1
	s_lshl_b32 s12, s3, 3
	v_lshlrev_b32_e32 v49, 5, v128
	s_movk_i32 s3, 0x110
	v_mul_u32_u24_e32 v52, 0x84, v51
	v_add3_u32 v138, v145, v49, v116
	v_mad_u32_u24 v49, v128, s3, v145
	v_mul_u32_u24_e32 v50, 0x210, v149
	s_movk_i32 s3, 0xfef4
	v_lshlrev_b32_e32 v52, 2, v52
	v_add_u32_e32 v139, v49, v116
	v_mad_i32_i24 v49, v128, s3, v49
	v_lshlrev_b32_e32 v50, 2, v50
	v_add_u32_e32 v53, 0x210, v52
	v_add_u32_e32 v54, 0x420, v52
	s_load_dwordx16 s[68:83], s[0:1], 0x80
	v_add_u32_e32 v140, v49, v50
	v_add_u32_e32 v141, v49, v52
	v_add_u32_e32 v142, v49, v53
	v_add_u32_e32 v143, v49, v54
	v_or_b32_e32 v49, 0xc0, v144
	v_add_u32_e32 v49, v145, v49
	v_and_b32_e32 v136, 0x70, v150
	v_and_b32_e32 v48, 8, v151
	v_add_u32_e32 v150, v49, v50
	v_add_u32_e32 v151, v49, v52
	v_add_u32_e32 v152, v49, v53
	v_add_u32_e32 v153, v49, v54
	v_or_b32_e32 v49, 0x1c0, v144
	v_add_u32_e32 v49, v145, v49
	v_mov_b32_e32 v115, 0
	v_add_u32_e32 v154, v49, v50
	v_add_u32_e32 v155, v49, v52
	v_add_u32_e32 v156, v49, v53
	v_add_u32_e32 v157, v49, v54
	v_lshlrev_b32_e32 v49, 7, v149
	v_lshlrev_b32_e32 v50, 1, v128
	v_and_b32_e32 v114, 0x40000, v119
	s_waitcnt lgkmcnt(0)
	s_mov_b64 s[16:17], s[80:81]
	v_ashrrev_i32_e32 v113, 31, v112
	v_cmp_gt_u32_e64 s[4:5], 32, v118
	v_cmp_gt_u32_e32 vcc, 4, v128
	v_add3_u32 v149, v145, v49, v50
	v_lshlrev_b32_e32 v49, 5, v51
	v_lshl_add_u64 v[52:53], s[42:43], 0, v[114:115]
	v_mov_b32_e32 v51, v115
	v_lshlrev_b32_e32 v114, 2, v48
	v_mov_b32_e32 v117, v115
	s_mov_b64 s[18:19], s[82:83]
	v_lshlrev_b64 v[124:125], 8, v[112:113]
	s_ashr_i32 s13, s12, 31
	v_lshlrev_b32_e32 v137, 6, v128
	s_and_b64 s[14:15], s[4:5], vcc
	v_add_u32_e32 v158, v145, v144
	v_add3_u32 v159, v145, v49, v50
	v_add_u32_e32 v160, 64, v149
	v_add_u32_e32 v161, 0x60, v149
	v_cmp_gt_u32_e64 s[6:7], 16, v118
	v_lshl_add_u64 v[118:119], s[44:45], 0, v[50:51]
	v_lshl_add_u64 v[120:121], v[52:53], 0, v[114:115]
	v_lshl_add_u64 v[122:123], s[16:17], 0, v[116:117]
	v_lshl_add_u64 v[116:117], s[18:19], 0, v[116:117]
	v_or_b32_e32 v124, v124, v144
	s_lshl_b64 s[16:17], s[12:13], 8
	s_mov_b64 s[18:19], 0
	v_lshlrev_b32_e32 v126, 1, v48
	v_add_u32_e32 v113, v145, v148
	s_movk_i32 s3, 0x1fff
	s_load_dwordx4 s[88:91], s[0:1], 0x18
	s_waitcnt lgkmcnt(0)
	v_lshl_add_u64 v[218:219], s[88:89], 0, v[124:125]
	global_load_dword v216, v[218:219], off
	v_lshl_add_u64 v[218:219], s[90:91], 0, v[124:125]
	global_load_dword v217, v[218:219], off
	v_ashrrev_i32_e32 v218, 4, v112
	v_and_b32_e32 v218, -4, v218
	v_add_u32_e32 v218, 0x4000, v218
	v_and_b32_e32 v222, 63, v112
	v_lshlrev_b32_e32 v222, 4, v222
	v_mov_b32_e32 v223, 0
	v_mov_b32_e32 v220, v126
	v_mov_b32_e32 v221, 0
	v_mov_b32_e32 v212, 0
	v_mov_b32_e32 v213, 0
	v_mov_b32_e32 v214, 0
	v_mov_b32_e32 v215, 0
	s_and_saveexec_b64 s[22:23], s[14:15]
	v_or_b32_e32 v218, v218, v128
	v_ashrrev_i32_e32 v219, 31, v218
	v_lshlrev_b64 v[218:219], 11, v[218:219]
	v_lshl_add_u64 v[218:219], s[46:47], 0, v[218:219]
	v_lshl_add_u64 v[218:219], v[222:223], 1, v[218:219]
	v_lshl_add_u64 v[218:219], v[218:219], 0, v[220:221]
	global_load_dwordx4 v[212:215], v[218:219], off
	s_or_b64 exec, exec, s[22:23]
	s_waitcnt vmcnt(0)
	s_branch .LBB0_1021

.LBB0_1025:
	s_waitcnt lgkmcnt(0)
	v_ashrrev_i32_e32 v0, 4, v112
	v_and_b32_e32 v0, -4, v0
	v_add_u32_e32 v4, 0x4000, v0
.LBB0_1027:
	s_waitcnt vmcnt(6)
	v_mov_b32_e32 v0, v212
	v_mov_b32_e32 v1, v213
	v_mov_b32_e32 v2, v214
	v_mov_b32_e32 v3, v215
	v_mov_b32_e32 v7, v216
	v_mov_b32_e32 v6, v217
	v_readfirstlane_b32 s22, v112
	s_add_i32 s22, s22, s12
	s_cmp_gt_i32 s22, s3
	s_cbranch_scc1 .Ls5g_nopf
	v_add_u32_e32 v224, s12, v112
	v_lshl_add_u64 v[226:227], v[124:125], 0, s[16:17]
	v_lshl_add_u64 v[218:219], s[88:89], 0, v[226:227]
	global_load_dword v216, v[218:219], off
	v_lshl_add_u64 v[218:219], s[90:91], 0, v[226:227]
	global_load_dword v217, v[218:219], off
	v_ashrrev_i32_e32 v218, 4, v224
	v_and_b32_e32 v218, -4, v218
	v_add_u32_e32 v218, 0x4000, v218
	v_and_b32_e32 v222, 63, v224
	v_lshlrev_b32_e32 v222, 4, v222
	v_mov_b32_e32 v223, 0
	v_mov_b32_e32 v220, v126
	v_mov_b32_e32 v221, 0
	v_mov_b32_e32 v212, 0
	v_mov_b32_e32 v213, 0
	v_mov_b32_e32 v214, 0
	v_mov_b32_e32 v215, 0
	s_and_saveexec_b64 s[22:23], s[14:15]
	v_or_b32_e32 v218, v218, v128
	v_ashrrev_i32_e32 v219, 31, v218
	v_lshlrev_b64 v[218:219], 11, v[218:219]
	v_lshl_add_u64 v[218:219], s[46:47], 0, v[218:219]
	v_lshl_add_u64 v[218:219], v[222:223], 1, v[218:219]
	v_lshl_add_u64 v[218:219], v[218:219], 0, v[220:221]
	global_load_dwordx4 v[212:215], v[218:219], off
	s_or_b64 exec, exec, s[22:23]
.Ls5g_nopf:
	v_mfma_f32_16x16x32_bf16 v[8:11], v[0:3], v[48:51], 0
	s_nop 7
	ds_write_b32 v140, v8
	ds_write_b32 v141, v9
	ds_write_b32 v142, v10
	ds_write_b32 v143, v11
	v_mfma_f32_16x16x32_bf16 v[8:11], v[0:3], v[52:55], 0
	s_nop 7
	ds_write_b32 v140, v8 offset:64
	ds_write_b32 v141, v9 offset:64
	ds_write_b32 v142, v10 offset:64
	ds_write_b32 v143, v11 offset:64
	v_mfma_f32_16x16x32_bf16 v[8:11], v[0:3], v[56:59], 0
	s_nop 7
	ds_write_b32 v140, v8 offset:128
	ds_write_b32 v141, v9 offset:128
	ds_write_b32 v142, v10 offset:128
	ds_write_b32 v143, v11 offset:128
	v_mfma_f32_16x16x32_bf16 v[8:11], v[0:3], v[60:63], 0
	s_nop 7
	ds_write_b32 v150, v8
	ds_write_b32 v151, v9
	ds_write_b32 v152, v10
	ds_write_b32 v153, v11
	v_mfma_f32_16x16x32_bf16 v[8:11], v[0:3], v[64:67], 0
	s_nop 7
	ds_write_b32 v140, v8 offset:256
	ds_write_b32 v141, v9 offset:256
	ds_write_b32 v142, v10 offset:256
	ds_write_b32 v143, v11 offset:256
	v_mfma_f32_16x16x32_bf16 v[8:11], v[0:3], v[68:71], 0
	s_nop 7
	ds_write_b32 v140, v8 offset:320
	ds_write_b32 v141, v9 offset:320
	ds_write_b32 v142, v10 offset:320
	ds_write_b32 v143, v11 offset:320
	v_mfma_f32_16x16x32_bf16 v[8:11], v[0:3], v[72:75], 0
	s_nop 7
	ds_write_b32 v140, v8 offset:384
	ds_write_b32 v141, v9 offset:384
	ds_write_b32 v142, v10 offset:384
	ds_write_b32 v143, v11 offset:384
	v_mfma_f32_16x16x32_bf16 v[8:11], v[0:3], v[80:83], 0
	s_nop 7
	ds_write_b32 v154, v8
	ds_write_b32 v155, v9
	ds_write_b32 v156, v10
	ds_write_b32 v157, v11
	s_and_saveexec_b64 s[20:21], s[4:5]
	ds_write_b128 v138, v[0:3] offset:12800
	s_or_b64 exec, exec, s[20:21]
	s_waitcnt lgkmcnt(0)
	ds_read2_b64 v[0:3], v113 offset1:66
	ds_read2_b64 v[8:11], v113 offset0:132 offset1:198
	v_mul_f32_e32 v12, v135, v7
	v_pk_fma_f32 v[12:13], v[134:135], v[6:7], v[12:13] op_sel_hi:[1,1,0] neg_lo:[1,0,0] neg_hi:[1,0,0]
	v_mov_b32_e32 v14, v7
	v_mov_b32_e32 v15, v6
	v_mul_f32_e32 v6, v134, v7
	v_pk_fma_f32 v[6:7], v[134:135], v[14:15], v[6:7] op_sel_hi:[1,1,0]
	s_nop 0
	v_mov_b32_e32 v13, v7
	s_waitcnt lgkmcnt(1)
	v_pk_add_f32 v[0:1], v[12:13], v[0:1]
	s_nop 0
	v_mul_f32_e32 v6, v134, v1
	v_mul_f32_e32 v12, v134, v0
	v_cvt_pk_bf16_f32 v5, v0, v1
	v_pk_fma_f32 v[6:7], v[134:135], v[0:1], v[6:7] op_sel:[1,0,0] op_sel_hi:[0,1,0] neg_lo:[0,0,1] neg_hi:[0,0,1]
	v_pk_fma_f32 v[0:1], v[134:135], v[0:1], v[12:13] op_sel_hi:[1,1,0]
	s_nop 0
	v_mov_b32_e32 v7, v1
	v_pk_add_f32 v[0:1], v[2:3], v[6:7]
	v_add_u32_e32 v3, 0x2000, v158
	v_cvt_pk_bf16_f32 v2, v0, v1
	ds_write2_b32 v3, v5, v2 offset0:64 offset1:132
	v_mul_f32_e32 v2, v134, v1
	v_mul_f32_e32 v6, v134, v0
	v_pk_fma_f32 v[2:3], v[134:135], v[0:1], v[2:3] op_sel:[1,0,0] op_sel_hi:[0,1,0] neg_lo:[0,0,1] neg_hi:[0,0,1]
	v_pk_fma_f32 v[0:1], v[134:135], v[0:1], v[6:7] op_sel_hi:[1,1,0]
	s_nop 0
	v_mov_b32_e32 v3, v1
	s_waitcnt lgkmcnt(1)
	v_pk_add_f32 v[0:1], v[8:9], v[2:3]
	s_nop 0
	v_pk_mul_f32 v[2:3], v[134:135], v[0:1] op_sel:[1,0] op_sel_hi:[0,1]
	v_sub_f32_e32 v2, v2, v3
	v_add_f32_e32 v8, v10, v2
	v_mul_f32_e32 v2, v135, v1
	v_cvt_pk_bf16_f32 v5, v0, v1
	v_pk_fma_f32 v[0:1], v[134:135], v[0:1], v[2:3] op_sel_hi:[1,1,0]
	s_nop 0
	v_pk_add_f32 v[6:7], v[10:11], v[0:1] op_sel:[1,0] op_sel_hi:[0,1]
	v_cvt_pk_bf16_f32 v0, v8, v6
	v_add_u32_e32 v1, 0x2200, v158
	ds_write2_b32 v1, v5, v0 offset0:72 offset1:140
	v_add_u32_e32 v1, 0x2400, v158
	ds_write2_b32 v1, v0, v0 offset0:80 offset1:148
	v_add_u32_e32 v1, 0x2600, v158
	ds_write2_b32 v1, v0, v0 offset0:88 offset1:156
	v_add_u32_e32 v1, 0x2800, v158
	ds_write2_b32 v1, v0, v0 offset0:96 offset1:164
	v_add_u32_e32 v1, 0x2a00, v158
	ds_write2_b32 v1, v0, v0 offset0:104 offset1:172
	v_add_u32_e32 v1, 0x2c00, v158
	ds_write2_b32 v1, v0, v0 offset0:112 offset1:180
	v_add_u32_e32 v1, 0x2e00, v158
	ds_write2_b32 v1, v0, v0 offset0:120 offset1:188
	s_waitcnt lgkmcnt(0)
	ds_read_b128 v[0:3], v139 offset:8448
	ds_read_b128 v[10:13], v139 offset:8512
	s_waitcnt lgkmcnt(1)
	v_mfma_f32_16x16x32_bf16 v[0:3], v[0:3], v[108:111], 0
	ds_read_b128 v[14:17], v139 offset:8576
	s_waitcnt lgkmcnt(1)
	v_mfma_f32_16x16x32_bf16 v[0:3], v[10:13], v[104:107], v[0:3]
	ds_read_b128 v[10:13], v139 offset:8640
	s_waitcnt lgkmcnt(1)
	v_mfma_f32_16x16x32_bf16 v[0:3], v[14:17], v[100:103], v[0:3]
	s_waitcnt lgkmcnt(0)
	v_mfma_f32_16x16x32_bf16 v[0:3], v[10:13], v[96:99], v[0:3]
	s_and_saveexec_b64 s[20:21], s[6:7]
	s_cbranch_execz .LBB0_1020
	ds_read_u16 v5, v149 offset:12800
	ds_read_u16 v7, v159 offset:12800
	ds_read_u16 v9, v160 offset:12800
	ds_read_u16 v12, v161 offset:12800
	v_lshl_add_u64 v[10:11], v[114:115], 1, v[118:119]
	s_waitcnt lgkmcnt(3)
	v_lshlrev_b32_e32 v5, 16, v5
	v_fma_f32 v0, v145, v5, v0
	v_mul_f32_e32 v5, 0x3d372713, v0
	v_mul_f32_e32 v5, v0, v5
	v_fma_f32 v5, v0, v5, v0
	v_mul_f32_e32 v5, 0xbfcc422a, v5
	v_mul_f32_e32 v5, 0x3fb8aa3b, v5
	v_exp_f32_e32 v5, v5
	s_waitcnt lgkmcnt(2)
	v_lshlrev_b32_e32 v7, 16, v7
	v_fma_f32 v7, v145, v7, v1
	v_add_f32_e32 v5, 1.0, v5
	v_div_scale_f32 v13, s[26:27], v5, v5, v0
	v_rcp_f32_e32 v14, v13
	v_div_scale_f32 v1, vcc, v0, v5, v0
	v_fma_f32 v15, -v13, v14, 1.0
	v_fmac_f32_e32 v14, v15, v14
	v_mul_f32_e32 v15, v1, v14
	v_fma_f32 v16, -v13, v15, v1
	v_fmac_f32_e32 v15, v16, v14
	v_fma_f32 v1, -v13, v15, v1
	v_mul_f32_e32 v13, 0x3d372713, v7
	v_mul_f32_e32 v13, v7, v13
	v_fma_f32 v13, v7, v13, v7
	v_mul_f32_e32 v13, 0xbfcc422a, v13
	v_mul_f32_e32 v13, 0x3fb8aa3b, v13
	v_exp_f32_e32 v13, v13
	v_div_fmas_f32 v1, v1, v14, v15
	v_div_fixup_f32 v0, v1, v5, v0
	v_ashrrev_i32_e32 v5, 31, v4
	v_add_f32_e32 v13, 1.0, v13
	v_div_scale_f32 v15, s[26:27], v13, v13, v7
	v_rcp_f32_e32 v16, v15
	v_cvt_pk_bf16_f32 v14, v0, s0
	v_lshlrev_b64 v[0:1], 11, v[4:5]
	v_lshl_add_u64 v[0:1], v[10:11], 0, v[0:1]
	global_store_short v[0:1], v14, off
	v_fma_f32 v0, -v15, v16, 1.0
	v_fmac_f32_e32 v16, v0, v16
	v_div_scale_f32 v0, vcc, v7, v13, v7
	v_mul_f32_e32 v1, v0, v16
	v_fma_f32 v5, -v15, v1, v0
	v_fmac_f32_e32 v1, v5, v16
	v_fma_f32 v0, -v15, v1, v0
	v_div_fmas_f32 v0, v0, v16, v1
	s_waitcnt lgkmcnt(1)
	v_lshlrev_b32_e32 v1, 16, v9
	v_fma_f32 v2, v145, v1, v2
	v_mul_f32_e32 v1, 0x3d372713, v2
	v_mul_f32_e32 v1, v2, v1
	v_fma_f32 v1, v2, v1, v2
	v_mul_f32_e32 v1, 0xbfcc422a, v1
	v_mul_f32_e32 v1, 0x3fb8aa3b, v1
	v_exp_f32_e32 v5, v1
	v_div_fixup_f32 v0, v0, v13, v7
	v_cvt_pk_bf16_f32 v7, v0, s0
	v_or_b32_e32 v0, 1, v4
	v_add_f32_e32 v5, 1.0, v5
	v_div_scale_f32 v9, s[26:27], v5, v5, v2
	v_rcp_f32_e32 v13, v9
	v_ashrrev_i32_e32 v1, 31, v0
	v_lshlrev_b64 v[0:1], 11, v[0:1]
	v_lshl_add_u64 v[0:1], v[10:11], 0, v[0:1]
	global_store_short v[0:1], v7, off
	v_fma_f32 v0, -v9, v13, 1.0
	v_fmac_f32_e32 v13, v0, v13
	v_div_scale_f32 v0, vcc, v2, v5, v2
	v_mul_f32_e32 v1, v0, v13
	v_fma_f32 v7, -v9, v1, v0
	v_fmac_f32_e32 v1, v7, v13
	v_fma_f32 v0, -v9, v1, v0
	v_div_fmas_f32 v0, v0, v13, v1
	s_waitcnt lgkmcnt(0)
	v_lshlrev_b32_e32 v1, 16, v12
	v_fmac_f32_e32 v3, v145, v1
	v_mul_f32_e32 v1, 0x3d372713, v3
	v_mul_f32_e32 v1, v3, v1
	v_fma_f32 v1, v3, v1, v3
	v_mul_f32_e32 v1, 0xbfcc422a, v1
	v_mul_f32_e32 v1, 0x3fb8aa3b, v1
	v_div_fixup_f32 v0, v0, v5, v2
	v_exp_f32_e32 v2, v1
	v_cvt_pk_bf16_f32 v5, v0, s0
	v_or_b32_e32 v0, 2, v4
	v_ashrrev_i32_e32 v1, 31, v0
	v_add_f32_e32 v2, 1.0, v2
	v_div_scale_f32 v7, s[26:27], v2, v2, v3
	v_rcp_f32_e32 v9, v7
	v_lshlrev_b64 v[0:1], 11, v[0:1]
	v_lshl_add_u64 v[0:1], v[10:11], 0, v[0:1]
	global_store_short v[0:1], v5, off
	v_fma_f32 v0, -v7, v9, 1.0
	v_fmac_f32_e32 v9, v0, v9
	v_div_scale_f32 v0, vcc, v3, v2, v3
	v_mul_f32_e32 v1, v0, v9
	v_fma_f32 v5, -v7, v1, v0
	v_fmac_f32_e32 v1, v5, v9
	v_fma_f32 v0, -v7, v1, v0
	v_div_fmas_f32 v0, v0, v9, v1
	v_div_fixup_f32 v0, v0, v2, v3
	v_cvt_pk_bf16_f32 v2, v0, s0
	v_or_b32_e32 v0, 3, v4
	v_ashrrev_i32_e32 v1, 31, v0
	v_lshlrev_b64 v[0:1], 11, v[0:1]
	v_lshl_add_u64 v[0:1], v[10:11], 0, v[0:1]
	global_store_short v[0:1], v2, off
	s_branch .LBB0_1020
